# one static s_setprio 1 for waves 4-7 during the GUP phase (on top of no per-phase setprio)
# speedup vs baseline: 1.0023x; 1.0023x over previous
.LBB0_237:
	s_add_u32 s68, s24, 0x19b69c00
	s_addc_u32 s69, s25, 0
	s_and_b32 s18, s6, 3
	s_add_i32 m0, s81, 0x18000
	v_lshl_add_u64 v[8:9], v[8:9], 0, s[34:35]
	s_lshl_b32 s6, s15, 13
	s_lshl_b32 s21, s18, 12
	s_waitcnt vmcnt(2)
	s_barrier
	global_load_lds_dwordx4 v[8:9], off
	v_lshl_add_u64 v[6:7], v[6:7], 0, s[34:35]
	s_add_i32 m0, s81, 0x1a000
	s_add_i32 s19, s81, 0x8000
	s_add_i32 s20, s81, 0xa000
	global_load_lds_dwordx4 v[6:7], off
	v_lshl_add_u64 v[2:3], v[2:3], 0, s[34:35]
	s_mov_b32 m0, s19
	s_add_u32 s22, s92, 0x40080
	global_load_lds_dwordx4 v[2:3], off
	v_lshl_add_u64 v[2:3], v[4:5], 0, s[34:35]
	s_mov_b32 m0, s20
	s_addc_u32 s23, s93, 0
	global_load_lds_dwordx4 v[2:3], off
	s_add_i32 m0, s81, 0x1c000
	v_lshl_add_u64 v[2:3], s[22:23], 0, v[164:165]
	global_load_lds_dwordx4 v[2:3], off
	v_lshl_add_u64 v[2:3], s[22:23], 0, v[168:169]
	s_add_i32 m0, s81, 0x1e000
	v_bfe_u32 v179, v208, 4, 2
	global_load_lds_dwordx4 v[2:3], off
	v_lshlrev_b32_e32 v2, 6, v177
	v_lshlrev_b32_e32 v3, 2, v177
	v_lshl_or_b32 v2, v179, 4, v2
	v_and_b32_e32 v3, 32, v3
	v_bitop3_b32 v4, s6, v2, v3 bitop3:0xf6
	v_bitop3_b32 v181, s21, v2, v3 bitop3:0xf6
	v_lshlrev_b32_e32 v2, 14, v0
	v_and_b32_e32 v2, 0xffff8000, v2
	v_lshl_add_u32 v2, v10, 11, v2
	v_and_b32_e32 v0, 1, v0
	s_cmpk_lt_u32 s2, 0x100
	v_lshl_or_b32 v0, v0, 6, v2
	s_cselect_b64 s[74:75], -1, 0
	s_ashr_i32 s21, s12, 31
	s_ashr_i32 s22, s28, 31
	v_lshl_add_u32 v170, v11, 1, v0
	v_lshlrev_b32_e32 v0, 14, v12
	s_add_u32 s78, s44, 0x2c00
	v_and_b32_e32 v0, 0xffff8000, v0
	s_waitcnt vmcnt(6)
	s_addc_u32 s79, s45, 0
	v_lshl_add_u32 v0, v13, 11, v0
	v_and_b32_e32 v2, 1, v12
	s_add_u32 s26, s44, 0x5800
	v_lshl_or_b32 v0, v2, 6, v0
	s_addc_u32 s27, s45, 0
	v_mov_b32_e32 v171, v1
	v_lshl_add_u32 v172, v14, 1, v0
	v_mov_b32_e32 v173, v1
	s_mov_b32 s23, 0
	v_add_u32_e32 v189, 0, v4
	s_barrier
	s_andn2_b64 vcc, exec, s[62:63]
	s_cbranch_vccnz .Lgup_noprio
	s_setprio 1
.Lgup_noprio:
	s_branch .LBB0_240
.LBB0_238:
	s_mov_b64 s[38:39], 0

.LBB0_272:
	s_setprio 0
	s_load_dwordx4 s[72:75], s[0:1], 0x68
	s_waitcnt vmcnt(0)
	v_readlane_b32 s96, v255, 17
	v_readlane_b32 s22, v255, 19
	v_readlane_b32 s70, v255, 16
	v_readlane_b32 s97, v255, 18
	v_readlane_b32 s23, v255, 20
	s_mov_b32 s71, 0x1e17a400
	s_waitcnt lgkmcnt(0)
	s_movk_i32 s72, 0x2000
	s_movk_i32 s83, 0x1ff
	s_mov_b32 s20, 0xb000
	s_barrier
